# v54 + P2 rope epilogue: all 16 rope-table loads issued at the epilogue start into dead fragment regs; per-chunk waits vmcnt(15)/(14) instead of vmcnt(1)/(0) after the chunk's own stores
# speedup vs baseline: 1.0014x; 1.0014x over previous
; __device__ __forceinline__ unsigned pk2(float lo, float hi) { f32x2 v = {lo, hi}; nbf2 r = __builtin_convertvector(v, nbf2); return __builtin_bit_cast(unsigned, r); }
;     __device__ __forceinline__ void operator()(f32x4 (&acc)[2][2][4][2], const pg8::Unit& u, int wr, int wc, int fr, int fq, LAS unsigned char* lds) const {
;     ...
;                 const int r = u.pm * 256 + ai * 128 + wr * 64 + m * 16 + fr;
;                 const bool lat = r < NLAT;
;                 const int t = r & (SEQ - 1);
;                 const int val = (wc & 1) ? (t & 63) : (t >> 6);
;                 const f32x4 cs = *(const f32x4*)(rope + val * 32 + 4 * fq), sn = *(const f32x4*)(rope + val * 32 + 16 + 4 * fq);
;                 bf16_t* rowp = O + (size_t)r * NQKVZ;
; #pragma unroll
;                 for (int bj = 0; bj < 2; ++bj) {
;                     const int cb = u.pn * 256 + bj * 128 + wc * 32;
;                     f32x4 t1 = acc[ai][bj][m][0], t2 = acc[ai][bj][m][1];
;                     if (cb < 1280 && lat) { const f32x4 o1 = t1 * cs - t2 * sn, o2 = t2 * cs + t1 * sn; t1 = o1; t2 = o2; }
;                     if (cb < 1024) { t1 = t1 * qs; t2 = t2 * qs; }
;                     u32x4 w; w.x = pk2(t1[0], t1[1]); w.y = pk2(t1[2], t1[3]); w.z = pk2(t2[0], t2[1]); w.w = pk2(t2[2], t2[3]);
;                     *(u32x4*)(rowp + cb + 8 * fq) = w;
.LBB0_188:
	s_lshl_b32 s96, s1, 8
	s_or_b32 s96, s96, s83
	s_cmpk_ge_i32 s96, 0x500
	s_cbranch_scc1 .Lqkvz_plain
	s_lshl_b32 s55, s0, 8
	s_add_i32 s55, s55, s82
	s_bfe_u32 s0, s55, 0x60006
	v_mov_b32_e32 v158, s0
	v_cndmask_b32_e64 v136, v150, v158, s[2:3]
	v_lshlrev_b32_e32 v136, 7, v136
	v_lshl_add_u64 v[164:165], v[140:141], 0, v[136:137]
	s_add_i32 s96, s55, 0x80
	s_bfe_u32 s96, s96, 0x60006
	v_mov_b32_e32 v184, s96
	v_mov_b32_e32 v191, 0
	v_cndmask_b32_e64 v190, v150, v158, s[2:3]
	v_lshlrev_b32_e32 v190, 7, v190
	v_lshl_add_u64 v[254:255], v[140:141], 0, v[190:191]
	global_load_dwordx4 v[186:189], v[254:255], off offset:64
	global_load_dwordx4 v[194:197], v[254:255], off
	v_cndmask_b32_e64 v190, v152, v158, s[2:3]
	v_lshlrev_b32_e32 v190, 7, v190
	v_lshl_add_u64 v[254:255], v[140:141], 0, v[190:191]
	global_load_dwordx4 v[198:201], v[254:255], off offset:64
	global_load_dwordx4 v[202:205], v[254:255], off
	v_cndmask_b32_e64 v190, v153, v158, s[2:3]
	v_lshlrev_b32_e32 v190, 7, v190
	v_lshl_add_u64 v[254:255], v[140:141], 0, v[190:191]
	global_load_dwordx4 v[206:209], v[254:255], off offset:64
	global_load_dwordx4 v[210:213], v[254:255], off
	v_cndmask_b32_e64 v190, v154, v158, s[2:3]
	v_lshlrev_b32_e32 v190, 7, v190
	v_lshl_add_u64 v[254:255], v[140:141], 0, v[190:191]
	global_load_dwordx4 v[214:217], v[254:255], off offset:64
	global_load_dwordx4 v[218:221], v[254:255], off
	v_cndmask_b32_e64 v190, v150, v184, s[2:3]
	v_lshlrev_b32_e32 v190, 7, v190
	v_lshl_add_u64 v[254:255], v[140:141], 0, v[190:191]
	global_load_dwordx4 v[222:225], v[254:255], off offset:64
	global_load_dwordx4 v[226:229], v[254:255], off
	v_cndmask_b32_e64 v190, v152, v184, s[2:3]
	v_lshlrev_b32_e32 v190, 7, v190
	v_lshl_add_u64 v[254:255], v[140:141], 0, v[190:191]
	global_load_dwordx4 v[230:233], v[254:255], off offset:64
	global_load_dwordx4 v[234:237], v[254:255], off
	v_cndmask_b32_e64 v190, v153, v184, s[2:3]
	v_lshlrev_b32_e32 v190, 7, v190
	v_lshl_add_u64 v[254:255], v[140:141], 0, v[190:191]
	global_load_dwordx4 v[238:241], v[254:255], off offset:64
	global_load_dwordx4 v[242:245], v[254:255], off
	v_cndmask_b32_e64 v190, v154, v184, s[2:3]
	v_lshlrev_b32_e32 v190, 7, v190
	v_lshl_add_u64 v[254:255], v[140:141], 0, v[190:191]
	global_load_dwordx4 v[246:249], v[254:255], off offset:64
	global_load_dwordx4 v[250:253], v[254:255], off
	s_lshl_b32 s0, s1, 8
	s_or_b32 s8, s0, s83
	v_or_b32_e32 v136, s55, v150
	s_cmpk_lt_i32 s8, 0x500
	v_cmp_gt_i32_e32 vcc, s81, v136
	v_mad_i64_i32 v[168:169], s[0:1], v136, s90, v[138:139]
	s_cselect_b64 s[64:65], -1, 0
	s_and_b64 s[0:1], s[64:65], vcc
	s_cmpk_lt_i32 s8, 0x400
	s_cselect_b64 s[6:7], -1, 0
	s_ashr_i32 s9, s8, 31
	s_lshl_b64 s[70:71], s[8:9], 1
	v_cndmask_b32_e64 v136, v152, v158, s[2:3]
	v_lshlrev_b32_e32 v136, 7, v136
	v_lshl_add_u64 v[170:171], v[140:141], 0, v[136:137]
	s_waitcnt vmcnt(14)
	v_pk_mul_f32 v[172:173], v[122:123], v[188:189]
	v_pk_mul_f32 v[174:175], v[120:121], v[186:187]
	v_pk_mul_f32 v[176:177], v[126:127], v[188:189]
	v_pk_mul_f32 v[178:179], v[124:125], v[186:187]
	v_pk_fma_f32 v[172:173], v[126:127], v[196:197], v[172:173] neg_lo:[0,0,1] neg_hi:[0,0,1]
	v_pk_fma_f32 v[174:175], v[124:125], v[194:195], v[174:175] neg_lo:[0,0,1] neg_hi:[0,0,1]
	v_pk_fma_f32 v[176:177], v[122:123], v[196:197], v[176:177]
	v_pk_fma_f32 v[178:179], v[120:121], v[194:195], v[178:179]
	v_cndmask_b32_e64 v127, v127, v173, s[0:1]
	v_cndmask_b32_e64 v126, v126, v172, s[0:1]
	v_cndmask_b32_e64 v125, v125, v175, s[0:1]
	v_cndmask_b32_e64 v124, v124, v174, s[0:1]
	v_cndmask_b32_e64 v123, v123, v177, s[0:1]
	v_cndmask_b32_e64 v122, v122, v176, s[0:1]
	v_cndmask_b32_e64 v121, v121, v179, s[0:1]
	v_cndmask_b32_e64 v120, v120, v178, s[0:1]
	s_or_b32 s0, s8, 0x80
	v_pk_mul_f32 v[180:181], v[114:115], v[188:189]
	v_pk_mul_f32 v[182:183], v[112:113], v[186:187]
	v_pk_mul_f32 v[162:163], v[118:119], v[188:189]
	v_pk_mul_f32 v[160:161], v[116:117], v[186:187]
	s_cmpk_lt_i32 s0, 0x500
	v_pk_fma_f32 v[180:181], v[118:119], v[196:197], v[180:181] neg_lo:[0,0,1] neg_hi:[0,0,1]
	v_pk_fma_f32 v[182:183], v[116:117], v[194:195], v[182:183] neg_lo:[0,0,1] neg_hi:[0,0,1]
	v_pk_fma_f32 v[162:163], v[114:115], v[196:197], v[162:163]
	v_pk_fma_f32 v[160:161], v[112:113], v[194:195], v[160:161]
	v_pk_mul_f32 v[164:165], v[126:127], s[50:51] op_sel_hi:[1,0]
	v_pk_mul_f32 v[166:167], v[124:125], s[50:51] op_sel_hi:[1,0]
	v_pk_mul_f32 v[172:173], v[120:121], s[50:51] op_sel_hi:[1,0]
	v_pk_mul_f32 v[174:175], v[122:123], s[50:51] op_sel_hi:[1,0]
	s_cselect_b64 s[66:67], -1, 0
	v_cndmask_b32_e64 v127, v127, v165, s[6:7]
	v_cndmask_b32_e64 v126, v126, v164, s[6:7]
	v_cndmask_b32_e64 v125, v125, v167, s[6:7]
	v_cndmask_b32_e64 v124, v124, v166, s[6:7]
	v_cndmask_b32_e64 v123, v123, v175, s[6:7]
	v_cndmask_b32_e64 v136, v122, v174, s[6:7]
	v_cndmask_b32_e64 v122, v121, v173, s[6:7]
	v_cndmask_b32_e64 v159, v120, v172, s[6:7]
	s_and_b64 vcc, s[66:67], vcc
	v_cvt_pk_bf16_f32 v120, v124, v125
	v_cvt_pk_bf16_f32 v121, v126, v127
	v_cvt_pk_bf16_f32 v122, v159, v122
	v_cvt_pk_bf16_f32 v123, v136, v123
	v_lshl_add_u64 v[124:125], v[168:169], 0, s[70:71]
	v_cndmask_b32_e32 v119, v119, v181, vcc
	v_cndmask_b32_e32 v118, v118, v180, vcc
	v_cndmask_b32_e32 v117, v117, v183, vcc
	v_cndmask_b32_e32 v116, v116, v182, vcc
	v_cndmask_b32_e32 v115, v115, v163, vcc
	v_cndmask_b32_e32 v114, v114, v162, vcc
	v_cndmask_b32_e32 v113, v113, v161, vcc
	v_cndmask_b32_e32 v112, v112, v160, vcc
	s_cmpk_lt_i32 s0, 0x400
	global_store_dwordx4 v[124:125], v[120:123], off
	v_pk_mul_f32 v[126:127], v[112:113], s[50:51] op_sel_hi:[1,0]
	v_pk_mul_f32 v[160:161], v[114:115], s[50:51] op_sel_hi:[1,0]
	v_pk_mul_f32 v[120:121], v[116:117], s[50:51] op_sel_hi:[1,0]
	v_pk_mul_f32 v[122:123], v[118:119], s[50:51] op_sel_hi:[1,0]
	s_cselect_b64 s[8:9], -1, 0
	v_cndmask_b32_e64 v119, v119, v123, s[8:9]
	v_cndmask_b32_e64 v118, v118, v122, s[8:9]
	v_cndmask_b32_e64 v117, v117, v121, s[8:9]
	v_cndmask_b32_e64 v116, v116, v120, s[8:9]
	v_cndmask_b32_e64 v115, v115, v161, s[8:9]
	v_cndmask_b32_e64 v120, v114, v160, s[8:9]
	v_cndmask_b32_e64 v114, v113, v127, s[8:9]
	v_cndmask_b32_e64 v121, v112, v126, s[8:9]
	v_cvt_pk_bf16_f32 v112, v116, v117
	v_cvt_pk_bf16_f32 v113, v118, v119
	v_cvt_pk_bf16_f32 v114, v121, v114
	v_cvt_pk_bf16_f32 v115, v120, v115
	global_store_dwordx4 v[124:125], v[112:115], off offset:256
	v_or_b32_e32 v120, s55, v152
	v_cmp_gt_i32_e32 vcc, s81, v120
	v_mad_i64_i32 v[120:121], s[0:1], v120, s90, v[138:139]
	s_and_b64 s[0:1], s[64:65], vcc
	s_and_b64 vcc, s[66:67], vcc
	v_cndmask_b32_e64 v122, v153, v158, s[2:3]
	v_lshlrev_b32_e32 v136, 7, v122
	v_lshl_add_u64 v[120:121], v[120:121], 0, s[70:71]
	v_lshl_add_u64 v[122:123], v[140:141], 0, v[136:137]
	s_waitcnt vmcnt(15)
; __device__ __forceinline__ unsigned pk2(float lo, float hi) { f32x2 v = {lo, hi}; nbf2 r = __builtin_convertvector(v, nbf2); return __builtin_bit_cast(unsigned, r); }
;     __device__ __forceinline__ void operator()(f32x4 (&acc)[2][2][4][2], const pg8::Unit& u, int wr, int wc, int fr, int fq, LAS unsigned char* lds) const {
;     ...
;                 const f32x4 cs = *(const f32x4*)(rope + val * 32 + 4 * fq), sn = *(const f32x4*)(rope + val * 32 + 16 + 4 * fq);
;                 bf16_t* rowp = O + (size_t)r * NQKVZ;
; #pragma unroll
;                 for (int bj = 0; bj < 2; ++bj) {
;                     const int cb = u.pn * 256 + bj * 128 + wc * 32;
;                     f32x4 t1 = acc[ai][bj][m][0], t2 = acc[ai][bj][m][1];
;                     if (cb < 1280 && lat) { const f32x4 o1 = t1 * cs - t2 * sn, o2 = t2 * cs + t1 * sn; t1 = o1; t2 = o2; }
;                     if (cb < 1024) { t1 = t1 * qs; t2 = t2 * qs; }
;                     u32x4 w; w.x = pk2(t1[0], t1[1]); w.y = pk2(t1[2], t1[3]); w.z = pk2(t2[0], t2[1]); w.w = pk2(t2[2], t2[3]);
;                     *(u32x4*)(rowp + cb + 8 * fq) = w;
	v_pk_mul_f32 v[124:125], v[106:107], v[200:201]
	v_pk_mul_f32 v[126:127], v[104:105], v[198:199]
	v_pk_mul_f32 v[160:161], v[110:111], v[200:201]
	v_pk_mul_f32 v[162:163], v[108:109], v[198:199]
	v_pk_mul_f32 v[164:165], v[98:99], v[200:201]
	v_pk_mul_f32 v[166:167], v[96:97], v[198:199]
	v_pk_mul_f32 v[114:115], v[102:103], v[200:201]
	v_pk_mul_f32 v[112:113], v[100:101], v[198:199]
	s_waitcnt vmcnt(14)
	v_pk_fma_f32 v[124:125], v[110:111], v[204:205], v[124:125] neg_lo:[0,0,1] neg_hi:[0,0,1]
	v_pk_fma_f32 v[126:127], v[108:109], v[202:203], v[126:127] neg_lo:[0,0,1] neg_hi:[0,0,1]
	v_pk_fma_f32 v[160:161], v[106:107], v[204:205], v[160:161]
	v_pk_fma_f32 v[162:163], v[104:105], v[202:203], v[162:163]
	v_pk_fma_f32 v[164:165], v[102:103], v[204:205], v[164:165] neg_lo:[0,0,1] neg_hi:[0,0,1]
	v_pk_fma_f32 v[166:167], v[100:101], v[202:203], v[166:167] neg_lo:[0,0,1] neg_hi:[0,0,1]
	v_pk_fma_f32 v[114:115], v[98:99], v[204:205], v[114:115]
	v_pk_fma_f32 v[112:113], v[96:97], v[202:203], v[112:113]
	v_cndmask_b32_e64 v111, v111, v125, s[0:1]
	v_cndmask_b32_e64 v110, v110, v124, s[0:1]
	v_cndmask_b32_e64 v109, v109, v127, s[0:1]
	v_cndmask_b32_e64 v108, v108, v126, s[0:1]
	v_cndmask_b32_e64 v107, v107, v161, s[0:1]
	v_cndmask_b32_e64 v106, v106, v160, s[0:1]
	v_cndmask_b32_e64 v105, v105, v163, s[0:1]
	v_cndmask_b32_e64 v104, v104, v162, s[0:1]
	v_cndmask_b32_e32 v103, v103, v165, vcc
	v_cndmask_b32_e32 v102, v102, v164, vcc
	v_cndmask_b32_e32 v101, v101, v167, vcc
	v_cndmask_b32_e32 v100, v100, v166, vcc
	v_cndmask_b32_e32 v99, v99, v115, vcc
	v_cndmask_b32_e32 v98, v98, v114, vcc
	v_cndmask_b32_e32 v97, v97, v113, vcc
	v_cndmask_b32_e32 v96, v96, v112, vcc
	v_pk_mul_f32 v[112:113], v[108:109], s[50:51] op_sel_hi:[1,0]
	v_pk_mul_f32 v[114:115], v[110:111], s[50:51] op_sel_hi:[1,0]
	v_pk_mul_f32 v[116:117], v[104:105], s[50:51] op_sel_hi:[1,0]
	v_pk_mul_f32 v[118:119], v[106:107], s[50:51] op_sel_hi:[1,0]
	v_pk_mul_f32 v[124:125], v[100:101], s[50:51] op_sel_hi:[1,0]
	v_pk_mul_f32 v[126:127], v[102:103], s[50:51] op_sel_hi:[1,0]
	v_pk_mul_f32 v[160:161], v[96:97], s[50:51] op_sel_hi:[1,0]
	v_pk_mul_f32 v[162:163], v[98:99], s[50:51] op_sel_hi:[1,0]
	v_cndmask_b32_e64 v111, v111, v115, s[6:7]
	v_cndmask_b32_e64 v110, v110, v114, s[6:7]
	v_cndmask_b32_e64 v109, v109, v113, s[6:7]
	v_cndmask_b32_e64 v108, v108, v112, s[6:7]
	v_cndmask_b32_e64 v107, v107, v119, s[6:7]
	v_cndmask_b32_e64 v106, v106, v118, s[6:7]
	v_cndmask_b32_e64 v105, v105, v117, s[6:7]
	v_cndmask_b32_e64 v104, v104, v116, s[6:7]
	v_cndmask_b32_e64 v103, v103, v127, s[8:9]
	v_cndmask_b32_e64 v102, v102, v126, s[8:9]
	v_cndmask_b32_e64 v101, v101, v125, s[8:9]
	v_cndmask_b32_e64 v100, v100, v124, s[8:9]
	v_cndmask_b32_e64 v112, v99, v163, s[8:9]
	v_cndmask_b32_e64 v113, v98, v162, s[8:9]
	v_cndmask_b32_e64 v114, v97, v161, s[8:9]
	v_cndmask_b32_e64 v115, v96, v160, s[8:9]
	v_cvt_pk_bf16_f32 v96, v108, v109
	v_cvt_pk_bf16_f32 v97, v110, v111
	v_cvt_pk_bf16_f32 v98, v104, v105
	v_cvt_pk_bf16_f32 v99, v106, v107
	v_cvt_pk_bf16_f32 v100, v100, v101
	v_cvt_pk_bf16_f32 v101, v102, v103
	v_cvt_pk_bf16_f32 v102, v115, v114
	v_cvt_pk_bf16_f32 v103, v113, v112
	global_store_dwordx4 v[120:121], v[96:99], off
	global_store_dwordx4 v[120:121], v[100:103], off offset:256
	v_or_b32_e32 v104, s55, v153
	v_cmp_gt_i32_e32 vcc, s81, v104
	v_mad_i64_i32 v[104:105], s[0:1], v104, s90, v[138:139]
	s_and_b64 s[0:1], s[64:65], vcc
	s_and_b64 vcc, s[66:67], vcc
	v_cndmask_b32_e64 v106, v154, v158, s[2:3]
	v_lshlrev_b32_e32 v136, 7, v106
	v_lshl_add_u64 v[104:105], v[104:105], 0, s[70:71]
	v_lshl_add_u64 v[106:107], v[140:141], 0, v[136:137]
	s_waitcnt vmcnt(15)
	v_pk_mul_f32 v[108:109], v[90:91], v[208:209]
	v_pk_mul_f32 v[110:111], v[88:89], v[206:207]
	v_pk_mul_f32 v[112:113], v[94:95], v[208:209]
	v_pk_mul_f32 v[114:115], v[92:93], v[206:207]
	v_pk_mul_f32 v[116:117], v[82:83], v[208:209]
	v_pk_mul_f32 v[118:119], v[80:81], v[206:207]
	v_pk_mul_f32 v[98:99], v[86:87], v[208:209]
	v_pk_mul_f32 v[96:97], v[84:85], v[206:207]
	s_waitcnt vmcnt(14)
	v_pk_fma_f32 v[108:109], v[94:95], v[212:213], v[108:109] neg_lo:[0,0,1] neg_hi:[0,0,1]
	v_pk_fma_f32 v[110:111], v[92:93], v[210:211], v[110:111] neg_lo:[0,0,1] neg_hi:[0,0,1]
	v_pk_fma_f32 v[112:113], v[90:91], v[212:213], v[112:113]
	v_pk_fma_f32 v[114:115], v[88:89], v[210:211], v[114:115]
	v_pk_fma_f32 v[116:117], v[86:87], v[212:213], v[116:117] neg_lo:[0,0,1] neg_hi:[0,0,1]
	v_pk_fma_f32 v[118:119], v[84:85], v[210:211], v[118:119] neg_lo:[0,0,1] neg_hi:[0,0,1]
	v_pk_fma_f32 v[98:99], v[82:83], v[212:213], v[98:99]
	v_pk_fma_f32 v[96:97], v[80:81], v[210:211], v[96:97]
	v_cndmask_b32_e64 v95, v95, v109, s[0:1]
	v_cndmask_b32_e64 v94, v94, v108, s[0:1]
	v_cndmask_b32_e64 v93, v93, v111, s[0:1]
	v_cndmask_b32_e64 v92, v92, v110, s[0:1]
	v_cndmask_b32_e64 v91, v91, v113, s[0:1]
	v_cndmask_b32_e64 v90, v90, v112, s[0:1]
	v_cndmask_b32_e64 v89, v89, v115, s[0:1]
	v_cndmask_b32_e64 v88, v88, v114, s[0:1]
	v_cndmask_b32_e32 v87, v87, v117, vcc
	v_cndmask_b32_e32 v86, v86, v116, vcc
	v_cndmask_b32_e32 v85, v85, v119, vcc
	v_cndmask_b32_e32 v84, v84, v118, vcc
	v_cndmask_b32_e32 v83, v83, v99, vcc
	v_cndmask_b32_e32 v82, v82, v98, vcc
	v_cndmask_b32_e32 v81, v81, v97, vcc
	v_cndmask_b32_e32 v80, v80, v96, vcc
	v_pk_mul_f32 v[96:97], v[92:93], s[50:51] op_sel_hi:[1,0]
	v_pk_mul_f32 v[98:99], v[94:95], s[50:51] op_sel_hi:[1,0]
	v_pk_mul_f32 v[100:101], v[88:89], s[50:51] op_sel_hi:[1,0]
	v_pk_mul_f32 v[102:103], v[90:91], s[50:51] op_sel_hi:[1,0]
	v_pk_mul_f32 v[108:109], v[84:85], s[50:51] op_sel_hi:[1,0]
	v_pk_mul_f32 v[110:111], v[86:87], s[50:51] op_sel_hi:[1,0]
; __device__ __forceinline__ unsigned pk2(float lo, float hi) { f32x2 v = {lo, hi}; nbf2 r = __builtin_convertvector(v, nbf2); return __builtin_bit_cast(unsigned, r); }
;     __device__ __forceinline__ void operator()(f32x4 (&acc)[2][2][4][2], const pg8::Unit& u, int wr, int wc, int fr, int fq, LAS unsigned char* lds) const {
;     ...
;                 const int r = u.pm * 256 + ai * 128 + wr * 64 + m * 16 + fr;
;                 const bool lat = r < NLAT;
;                 const int t = r & (SEQ - 1);
;                 const int val = (wc & 1) ? (t & 63) : (t >> 6);
;                 const f32x4 cs = *(const f32x4*)(rope + val * 32 + 4 * fq), sn = *(const f32x4*)(rope + val * 32 + 16 + 4 * fq);
;                 bf16_t* rowp = O + (size_t)r * NQKVZ;
; #pragma unroll
;                 for (int bj = 0; bj < 2; ++bj) {
;                     const int cb = u.pn * 256 + bj * 128 + wc * 32;
;                     f32x4 t1 = acc[ai][bj][m][0], t2 = acc[ai][bj][m][1];
;                     if (cb < 1280 && lat) { const f32x4 o1 = t1 * cs - t2 * sn, o2 = t2 * cs + t1 * sn; t1 = o1; t2 = o2; }
;                     if (cb < 1024) { t1 = t1 * qs; t2 = t2 * qs; }
;                     u32x4 w; w.x = pk2(t1[0], t1[1]); w.y = pk2(t1[2], t1[3]); w.z = pk2(t2[0], t2[1]); w.w = pk2(t2[2], t2[3]);
;                     *(u32x4*)(rowp + cb + 8 * fq) = w;
;                 }
	v_pk_mul_f32 v[112:113], v[80:81], s[50:51] op_sel_hi:[1,0]
	v_pk_mul_f32 v[114:115], v[82:83], s[50:51] op_sel_hi:[1,0]
	v_cndmask_b32_e64 v95, v95, v99, s[6:7]
	v_cndmask_b32_e64 v94, v94, v98, s[6:7]
	v_cndmask_b32_e64 v93, v93, v97, s[6:7]
	v_cndmask_b32_e64 v92, v92, v96, s[6:7]
	v_cndmask_b32_e64 v91, v91, v103, s[6:7]
	v_cndmask_b32_e64 v90, v90, v102, s[6:7]
	v_cndmask_b32_e64 v89, v89, v101, s[6:7]
	v_cndmask_b32_e64 v88, v88, v100, s[6:7]
	v_cndmask_b32_e64 v87, v87, v111, s[8:9]
	v_cndmask_b32_e64 v86, v86, v110, s[8:9]
	v_cndmask_b32_e64 v85, v85, v109, s[8:9]
	v_cndmask_b32_e64 v84, v84, v108, s[8:9]
	v_cndmask_b32_e64 v96, v83, v115, s[8:9]
	v_cndmask_b32_e64 v97, v82, v114, s[8:9]
	v_cndmask_b32_e64 v98, v81, v113, s[8:9]
	v_cndmask_b32_e64 v99, v80, v112, s[8:9]
	v_cvt_pk_bf16_f32 v80, v92, v93
	v_cvt_pk_bf16_f32 v81, v94, v95
	v_cvt_pk_bf16_f32 v82, v88, v89
	v_cvt_pk_bf16_f32 v83, v90, v91
	v_cvt_pk_bf16_f32 v84, v84, v85
	v_cvt_pk_bf16_f32 v85, v86, v87
	v_cvt_pk_bf16_f32 v86, v99, v98
	v_cvt_pk_bf16_f32 v87, v97, v96
	global_store_dwordx4 v[104:105], v[80:83], off
	global_store_dwordx4 v[104:105], v[84:87], off offset:256
	v_or_b32_e32 v80, s55, v154
	v_cmp_gt_i32_e32 vcc, s81, v80
	v_mad_i64_i32 v[80:81], s[0:1], v80, s90, v[138:139]
	s_addk_i32 s55, 0x80
	s_bfe_u32 s0, s55, 0x60006
	v_lshl_add_u64 v[90:91], v[80:81], 0, s[70:71]
	v_mov_b32_e32 v80, s0
	s_and_b64 s[0:1], s[64:65], vcc
	s_and_b64 vcc, s[66:67], vcc
	v_cndmask_b32_e64 v81, v150, v80, s[2:3]
	v_lshlrev_b32_e32 v136, 7, v81
	v_lshl_add_u64 v[92:93], v[140:141], 0, v[136:137]
	s_waitcnt vmcnt(15)
	v_pk_mul_f32 v[94:95], v[74:75], v[216:217]
	v_pk_mul_f32 v[96:97], v[72:73], v[214:215]
	v_pk_mul_f32 v[98:99], v[78:79], v[216:217]
	v_pk_mul_f32 v[100:101], v[76:77], v[214:215]
	v_pk_mul_f32 v[102:103], v[66:67], v[216:217]
	v_pk_mul_f32 v[104:105], v[64:65], v[214:215]
	v_pk_mul_f32 v[84:85], v[70:71], v[216:217]
	v_pk_mul_f32 v[82:83], v[68:69], v[214:215]
	s_waitcnt vmcnt(14)
	v_pk_fma_f32 v[94:95], v[78:79], v[220:221], v[94:95] neg_lo:[0,0,1] neg_hi:[0,0,1]
	v_pk_fma_f32 v[96:97], v[76:77], v[218:219], v[96:97] neg_lo:[0,0,1] neg_hi:[0,0,1]
	v_pk_fma_f32 v[98:99], v[74:75], v[220:221], v[98:99]
	v_pk_fma_f32 v[100:101], v[72:73], v[218:219], v[100:101]
	v_pk_fma_f32 v[102:103], v[70:71], v[220:221], v[102:103] neg_lo:[0,0,1] neg_hi:[0,0,1]
	v_pk_fma_f32 v[104:105], v[68:69], v[218:219], v[104:105] neg_lo:[0,0,1] neg_hi:[0,0,1]
	v_pk_fma_f32 v[84:85], v[66:67], v[220:221], v[84:85]
	v_pk_fma_f32 v[82:83], v[64:65], v[218:219], v[82:83]
	v_cndmask_b32_e64 v79, v79, v95, s[0:1]
	v_cndmask_b32_e64 v78, v78, v94, s[0:1]
	v_cndmask_b32_e64 v77, v77, v97, s[0:1]
	v_cndmask_b32_e64 v76, v76, v96, s[0:1]
	v_cndmask_b32_e64 v75, v75, v99, s[0:1]
	v_cndmask_b32_e64 v74, v74, v98, s[0:1]
	v_cndmask_b32_e64 v73, v73, v101, s[0:1]
	v_cndmask_b32_e64 v72, v72, v100, s[0:1]
	v_cndmask_b32_e32 v71, v71, v103, vcc
	v_cndmask_b32_e32 v70, v70, v102, vcc
	v_cndmask_b32_e32 v69, v69, v105, vcc
	v_cndmask_b32_e32 v68, v68, v104, vcc
	v_cndmask_b32_e32 v67, v67, v85, vcc
	v_cndmask_b32_e32 v66, v66, v84, vcc
	v_cndmask_b32_e32 v65, v65, v83, vcc
	v_cndmask_b32_e32 v64, v64, v82, vcc
	v_pk_mul_f32 v[82:83], v[76:77], s[50:51] op_sel_hi:[1,0]
	v_pk_mul_f32 v[84:85], v[78:79], s[50:51] op_sel_hi:[1,0]
	v_pk_mul_f32 v[86:87], v[72:73], s[50:51] op_sel_hi:[1,0]
	v_pk_mul_f32 v[88:89], v[74:75], s[50:51] op_sel_hi:[1,0]
	v_pk_mul_f32 v[94:95], v[68:69], s[50:51] op_sel_hi:[1,0]
	v_pk_mul_f32 v[96:97], v[70:71], s[50:51] op_sel_hi:[1,0]
	v_pk_mul_f32 v[98:99], v[64:65], s[50:51] op_sel_hi:[1,0]
	v_pk_mul_f32 v[100:101], v[66:67], s[50:51] op_sel_hi:[1,0]
	v_cndmask_b32_e64 v79, v79, v85, s[6:7]
	v_cndmask_b32_e64 v78, v78, v84, s[6:7]
	v_cndmask_b32_e64 v77, v77, v83, s[6:7]
	v_cndmask_b32_e64 v76, v76, v82, s[6:7]
	v_cndmask_b32_e64 v75, v75, v89, s[6:7]
	v_cndmask_b32_e64 v74, v74, v88, s[6:7]
	v_cndmask_b32_e64 v73, v73, v87, s[6:7]
	v_cndmask_b32_e64 v72, v72, v86, s[6:7]
	v_cndmask_b32_e64 v71, v71, v97, s[8:9]
	v_cndmask_b32_e64 v70, v70, v96, s[8:9]
	v_cndmask_b32_e64 v69, v69, v95, s[8:9]
	v_cndmask_b32_e64 v68, v68, v94, s[8:9]
	v_cndmask_b32_e64 v81, v67, v101, s[8:9]
	v_cndmask_b32_e64 v82, v66, v100, s[8:9]
	v_cndmask_b32_e64 v83, v65, v99, s[8:9]
	v_cndmask_b32_e64 v84, v64, v98, s[8:9]
	v_cvt_pk_bf16_f32 v64, v76, v77
	v_cvt_pk_bf16_f32 v65, v78, v79
	v_cvt_pk_bf16_f32 v66, v72, v73
	v_cvt_pk_bf16_f32 v67, v74, v75
	v_cvt_pk_bf16_f32 v68, v68, v69
	v_cvt_pk_bf16_f32 v69, v70, v71
	v_cvt_pk_bf16_f32 v70, v84, v83
	v_cvt_pk_bf16_f32 v71, v82, v81
	global_store_dwordx4 v[90:91], v[64:67], off
	global_store_dwordx4 v[90:91], v[68:71], off offset:256
	v_or_b32_e32 v72, s55, v150
	v_cmp_gt_i32_e32 vcc, s81, v72
	v_mad_i64_i32 v[72:73], s[0:1], v72, s90, v[138:139]
	s_and_b64 s[0:1], s[64:65], vcc
	s_and_b64 vcc, s[66:67], vcc
	v_cndmask_b32_e64 v74, v152, v80, s[2:3]
	v_lshl_add_u64 v[72:73], v[72:73], 0, s[70:71]
	v_lshlrev_b32_e32 v136, 7, v74
	v_lshl_add_u64 v[74:75], v[140:141], 0, v[136:137]
	s_waitcnt vmcnt(15)
	v_pk_mul_f32 v[76:77], v[58:59], v[224:225]
	v_pk_mul_f32 v[78:79], v[56:57], v[222:223]
	v_pk_mul_f32 v[82:83], v[62:63], v[224:225]
	v_pk_mul_f32 v[84:85], v[60:61], v[222:223]
	v_pk_mul_f32 v[86:87], v[50:51], v[224:225]
	v_pk_mul_f32 v[88:89], v[48:49], v[222:223]
	v_pk_mul_f32 v[66:67], v[54:55], v[224:225]
	v_pk_mul_f32 v[64:65], v[52:53], v[222:223]
	s_waitcnt vmcnt(14)
; __device__ __forceinline__ unsigned pk2(float lo, float hi) { f32x2 v = {lo, hi}; nbf2 r = __builtin_convertvector(v, nbf2); return __builtin_bit_cast(unsigned, r); }
;     __device__ __forceinline__ void operator()(f32x4 (&acc)[2][2][4][2], const pg8::Unit& u, int wr, int wc, int fr, int fq, LAS unsigned char* lds) const {
;     ...
;                 const int r = u.pm * 256 + ai * 128 + wr * 64 + m * 16 + fr;
;                 const bool lat = r < NLAT;
;                 const int t = r & (SEQ - 1);
;                 const int val = (wc & 1) ? (t & 63) : (t >> 6);
;                 const f32x4 cs = *(const f32x4*)(rope + val * 32 + 4 * fq), sn = *(const f32x4*)(rope + val * 32 + 16 + 4 * fq);
;                 bf16_t* rowp = O + (size_t)r * NQKVZ;
; #pragma unroll
;                 for (int bj = 0; bj < 2; ++bj) {
;                     const int cb = u.pn * 256 + bj * 128 + wc * 32;
;                     f32x4 t1 = acc[ai][bj][m][0], t2 = acc[ai][bj][m][1];
;                     if (cb < 1280 && lat) { const f32x4 o1 = t1 * cs - t2 * sn, o2 = t2 * cs + t1 * sn; t1 = o1; t2 = o2; }
;                     if (cb < 1024) { t1 = t1 * qs; t2 = t2 * qs; }
;                     u32x4 w; w.x = pk2(t1[0], t1[1]); w.y = pk2(t1[2], t1[3]); w.z = pk2(t2[0], t2[1]); w.w = pk2(t2[2], t2[3]);
;                     *(u32x4*)(rowp + cb + 8 * fq) = w;
;                 }
	v_pk_fma_f32 v[76:77], v[62:63], v[228:229], v[76:77] neg_lo:[0,0,1] neg_hi:[0,0,1]
	v_pk_fma_f32 v[78:79], v[60:61], v[226:227], v[78:79] neg_lo:[0,0,1] neg_hi:[0,0,1]
	v_pk_fma_f32 v[82:83], v[58:59], v[228:229], v[82:83]
	v_pk_fma_f32 v[84:85], v[56:57], v[226:227], v[84:85]
	v_pk_fma_f32 v[86:87], v[54:55], v[228:229], v[86:87] neg_lo:[0,0,1] neg_hi:[0,0,1]
	v_pk_fma_f32 v[88:89], v[52:53], v[226:227], v[88:89] neg_lo:[0,0,1] neg_hi:[0,0,1]
	v_pk_fma_f32 v[66:67], v[50:51], v[228:229], v[66:67]
	v_pk_fma_f32 v[64:65], v[48:49], v[226:227], v[64:65]
	v_cndmask_b32_e64 v63, v63, v77, s[0:1]
	v_cndmask_b32_e64 v62, v62, v76, s[0:1]
	v_cndmask_b32_e64 v61, v61, v79, s[0:1]
	v_cndmask_b32_e64 v60, v60, v78, s[0:1]
	v_cndmask_b32_e64 v59, v59, v83, s[0:1]
	v_cndmask_b32_e64 v58, v58, v82, s[0:1]
	v_cndmask_b32_e64 v57, v57, v85, s[0:1]
	v_cndmask_b32_e64 v56, v56, v84, s[0:1]
	v_cndmask_b32_e32 v55, v55, v87, vcc
	v_cndmask_b32_e32 v54, v54, v86, vcc
	v_cndmask_b32_e32 v53, v53, v89, vcc
	v_cndmask_b32_e32 v52, v52, v88, vcc
	v_cndmask_b32_e32 v51, v51, v67, vcc
	v_cndmask_b32_e32 v50, v50, v66, vcc
	v_cndmask_b32_e32 v49, v49, v65, vcc
	v_cndmask_b32_e32 v48, v48, v64, vcc
	v_pk_mul_f32 v[64:65], v[60:61], s[50:51] op_sel_hi:[1,0]
	v_pk_mul_f32 v[66:67], v[62:63], s[50:51] op_sel_hi:[1,0]
	v_pk_mul_f32 v[68:69], v[56:57], s[50:51] op_sel_hi:[1,0]
	v_pk_mul_f32 v[70:71], v[58:59], s[50:51] op_sel_hi:[1,0]
	v_pk_mul_f32 v[76:77], v[52:53], s[50:51] op_sel_hi:[1,0]
	v_pk_mul_f32 v[78:79], v[54:55], s[50:51] op_sel_hi:[1,0]
	v_pk_mul_f32 v[82:83], v[48:49], s[50:51] op_sel_hi:[1,0]
	v_pk_mul_f32 v[84:85], v[50:51], s[50:51] op_sel_hi:[1,0]
	v_cndmask_b32_e64 v63, v63, v67, s[6:7]
	v_cndmask_b32_e64 v62, v62, v66, s[6:7]
	v_cndmask_b32_e64 v61, v61, v65, s[6:7]
	v_cndmask_b32_e64 v60, v60, v64, s[6:7]
	v_cndmask_b32_e64 v59, v59, v71, s[6:7]
	v_cndmask_b32_e64 v58, v58, v70, s[6:7]
	v_cndmask_b32_e64 v57, v57, v69, s[6:7]
	v_cndmask_b32_e64 v56, v56, v68, s[6:7]
	v_cndmask_b32_e64 v55, v55, v79, s[8:9]
	v_cndmask_b32_e64 v54, v54, v78, s[8:9]
	v_cndmask_b32_e64 v53, v53, v77, s[8:9]
	v_cndmask_b32_e64 v52, v52, v76, s[8:9]
	v_cndmask_b32_e64 v64, v51, v85, s[8:9]
	v_cndmask_b32_e64 v65, v50, v84, s[8:9]
	v_cndmask_b32_e64 v66, v49, v83, s[8:9]
	v_cndmask_b32_e64 v67, v48, v82, s[8:9]
	v_cvt_pk_bf16_f32 v48, v60, v61
	v_cvt_pk_bf16_f32 v49, v62, v63
	v_cvt_pk_bf16_f32 v50, v56, v57
	v_cvt_pk_bf16_f32 v51, v58, v59
	v_cvt_pk_bf16_f32 v52, v52, v53
	v_cvt_pk_bf16_f32 v53, v54, v55
	v_cvt_pk_bf16_f32 v54, v67, v66
	v_cvt_pk_bf16_f32 v55, v65, v64
	global_store_dwordx4 v[72:73], v[48:51], off
	global_store_dwordx4 v[72:73], v[52:55], off offset:256
	v_or_b32_e32 v56, s55, v152
	v_cmp_gt_i32_e32 vcc, s81, v56
	v_mad_i64_i32 v[56:57], s[0:1], v56, s90, v[138:139]
	s_and_b64 s[0:1], s[64:65], vcc
	s_and_b64 vcc, s[66:67], vcc
	v_cndmask_b32_e64 v58, v153, v80, s[2:3]
	v_lshl_add_u64 v[56:57], v[56:57], 0, s[70:71]
	v_lshlrev_b32_e32 v136, 7, v58
	v_lshl_add_u64 v[58:59], v[140:141], 0, v[136:137]
	s_waitcnt vmcnt(15)
	v_pk_mul_f32 v[60:61], v[42:43], v[232:233]
	v_pk_mul_f32 v[62:63], v[40:41], v[230:231]
	v_pk_mul_f32 v[64:65], v[46:47], v[232:233]
	v_pk_mul_f32 v[66:67], v[44:45], v[230:231]
	v_pk_mul_f32 v[68:69], v[34:35], v[232:233]
	v_pk_mul_f32 v[70:71], v[32:33], v[230:231]
	v_pk_mul_f32 v[50:51], v[38:39], v[232:233]
	v_pk_mul_f32 v[48:49], v[36:37], v[230:231]
	s_waitcnt vmcnt(14)
	v_pk_fma_f32 v[60:61], v[46:47], v[236:237], v[60:61] neg_lo:[0,0,1] neg_hi:[0,0,1]
	v_pk_fma_f32 v[62:63], v[44:45], v[234:235], v[62:63] neg_lo:[0,0,1] neg_hi:[0,0,1]
	v_pk_fma_f32 v[64:65], v[42:43], v[236:237], v[64:65]
	v_pk_fma_f32 v[66:67], v[40:41], v[234:235], v[66:67]
	v_pk_fma_f32 v[68:69], v[38:39], v[236:237], v[68:69] neg_lo:[0,0,1] neg_hi:[0,0,1]
	v_pk_fma_f32 v[70:71], v[36:37], v[234:235], v[70:71] neg_lo:[0,0,1] neg_hi:[0,0,1]
	v_pk_fma_f32 v[50:51], v[34:35], v[236:237], v[50:51]
	v_pk_fma_f32 v[48:49], v[32:33], v[234:235], v[48:49]
	v_cndmask_b32_e64 v47, v47, v61, s[0:1]
	v_cndmask_b32_e64 v46, v46, v60, s[0:1]
	v_cndmask_b32_e64 v45, v45, v63, s[0:1]
	v_cndmask_b32_e64 v44, v44, v62, s[0:1]
	v_cndmask_b32_e64 v43, v43, v65, s[0:1]
	v_cndmask_b32_e64 v42, v42, v64, s[0:1]
	v_cndmask_b32_e64 v41, v41, v67, s[0:1]
	v_cndmask_b32_e64 v40, v40, v66, s[0:1]
	v_cndmask_b32_e32 v39, v39, v69, vcc
	v_cndmask_b32_e32 v38, v38, v68, vcc
	v_cndmask_b32_e32 v37, v37, v71, vcc
	v_cndmask_b32_e32 v36, v36, v70, vcc
	v_cndmask_b32_e32 v35, v35, v51, vcc
	v_cndmask_b32_e32 v34, v34, v50, vcc
	v_cndmask_b32_e32 v33, v33, v49, vcc
	v_cndmask_b32_e32 v32, v32, v48, vcc
	v_pk_mul_f32 v[48:49], v[44:45], s[50:51] op_sel_hi:[1,0]
	v_pk_mul_f32 v[50:51], v[46:47], s[50:51] op_sel_hi:[1,0]
	v_pk_mul_f32 v[52:53], v[40:41], s[50:51] op_sel_hi:[1,0]
	v_pk_mul_f32 v[54:55], v[42:43], s[50:51] op_sel_hi:[1,0]
	v_pk_mul_f32 v[60:61], v[36:37], s[50:51] op_sel_hi:[1,0]
	v_pk_mul_f32 v[62:63], v[38:39], s[50:51] op_sel_hi:[1,0]
	v_pk_mul_f32 v[64:65], v[32:33], s[50:51] op_sel_hi:[1,0]
	v_pk_mul_f32 v[66:67], v[34:35], s[50:51] op_sel_hi:[1,0]
	v_cndmask_b32_e64 v47, v47, v51, s[6:7]
	v_cndmask_b32_e64 v46, v46, v50, s[6:7]
	v_cndmask_b32_e64 v45, v45, v49, s[6:7]
	v_cndmask_b32_e64 v44, v44, v48, s[6:7]
	v_cndmask_b32_e64 v43, v43, v55, s[6:7]
	v_cndmask_b32_e64 v42, v42, v54, s[6:7]
	v_cndmask_b32_e64 v41, v41, v53, s[6:7]
	v_cndmask_b32_e64 v40, v40, v52, s[6:7]
	v_cndmask_b32_e64 v39, v39, v63, s[8:9]
	v_cndmask_b32_e64 v38, v38, v62, s[8:9]
	v_cndmask_b32_e64 v37, v37, v61, s[8:9]
	v_cndmask_b32_e64 v36, v36, v60, s[8:9]
	v_cndmask_b32_e64 v48, v35, v67, s[8:9]
	v_cndmask_b32_e64 v49, v34, v66, s[8:9]
	v_cndmask_b32_e64 v50, v33, v65, s[8:9]
	v_cndmask_b32_e64 v51, v32, v64, s[8:9]
	v_cvt_pk_bf16_f32 v32, v44, v45
	v_cvt_pk_bf16_f32 v33, v46, v47
	v_cvt_pk_bf16_f32 v34, v40, v41
	v_cvt_pk_bf16_f32 v35, v42, v43
	v_cvt_pk_bf16_f32 v36, v36, v37
	v_cvt_pk_bf16_f32 v37, v38, v39
	v_cvt_pk_bf16_f32 v38, v51, v50
	v_cvt_pk_bf16_f32 v39, v49, v48
	global_store_dwordx4 v[56:57], v[32:35], off
	global_store_dwordx4 v[56:57], v[36:39], off offset:256
	v_or_b32_e32 v40, s55, v153
	v_cmp_gt_i32_e32 vcc, s81, v40
	v_mad_i64_i32 v[40:41], s[0:1], v40, s90, v[138:139]
	s_and_b64 s[0:1], s[64:65], vcc
	s_and_b64 vcc, s[66:67], vcc
	v_cndmask_b32_e64 v42, v154, v80, s[2:3]
	v_lshl_add_u64 v[40:41], v[40:41], 0, s[70:71]
	v_lshlrev_b32_e32 v136, 7, v42
	v_lshl_add_u64 v[42:43], v[140:141], 0, v[136:137]
	s_waitcnt vmcnt(15)
; __device__ __forceinline__ unsigned pk2(float lo, float hi) { f32x2 v = {lo, hi}; nbf2 r = __builtin_convertvector(v, nbf2); return __builtin_bit_cast(unsigned, r); }
; #define PG8_BAR __builtin_amdgcn_s_barrier()
; template <class Epi, class Sched>
; __device__ __forceinline__ void gemm_phase(LAS unsigned char* lds, const Gemm g, const Sched& S, const Epi& E) {
;     ...
;         if (wr == 0) PG8_BAR;
;         E(acc, cur, wr, wc, fr, fq, lds);
;         if (!has_next) break;
; #pragma unroll
;         for (int a = 0; a < 2; ++a)
; #pragma unroll
;             for (int b = 0; b < 2; ++b)
; #pragma unroll
;                 for (int m = 0; m < 4; ++m)
; #pragma unroll
;                     for (int n = 0; n < 2; ++n) acc[a][b][m][n] = (f32x4){0.f, 0.f, 0.f, 0.f};
;         cur = nxt; cA = nA; cB = nB; ++ui;
;         if (wr == 1) PG8_BAR;
;     }
;     __device__ __forceinline__ void operator()(f32x4 (&acc)[2][2][4][2], const pg8::Unit& u, int wr, int wc, int fr, int fq, LAS unsigned char* lds) const {
;     ...
;                 const int r = u.pm * 256 + ai * 128 + wr * 64 + m * 16 + fr;
;                 const bool lat = r < NLAT;
;                 const int t = r & (SEQ - 1);
;                 const int val = (wc & 1) ? (t & 63) : (t >> 6);
;                 const f32x4 cs = *(const f32x4*)(rope + val * 32 + 4 * fq), sn = *(const f32x4*)(rope + val * 32 + 16 + 4 * fq);
;                 bf16_t* rowp = O + (size_t)r * NQKVZ;
; #pragma unroll
;                 for (int bj = 0; bj < 2; ++bj) {
;                     const int cb = u.pn * 256 + bj * 128 + wc * 32;
;                     f32x4 t1 = acc[ai][bj][m][0], t2 = acc[ai][bj][m][1];
;                     if (cb < 1280 && lat) { const f32x4 o1 = t1 * cs - t2 * sn, o2 = t2 * cs + t1 * sn; t1 = o1; t2 = o2; }
;                     if (cb < 1024) { t1 = t1 * qs; t2 = t2 * qs; }
;                     u32x4 w; w.x = pk2(t1[0], t1[1]); w.y = pk2(t1[2], t1[3]); w.z = pk2(t2[0], t2[1]); w.w = pk2(t2[2], t2[3]);
;                     *(u32x4*)(rowp + cb + 8 * fq) = w;
;                 }
	v_pk_mul_f32 v[44:45], v[26:27], v[240:241]
	v_pk_mul_f32 v[46:47], v[24:25], v[238:239]
	v_pk_mul_f32 v[48:49], v[30:31], v[240:241]
	v_pk_mul_f32 v[50:51], v[28:29], v[238:239]
	v_pk_mul_f32 v[52:53], v[18:19], v[240:241]
	v_pk_mul_f32 v[54:55], v[16:17], v[238:239]
	v_pk_mul_f32 v[34:35], v[22:23], v[240:241]
	v_pk_mul_f32 v[32:33], v[20:21], v[238:239]
	s_waitcnt vmcnt(14)
	v_pk_fma_f32 v[44:45], v[30:31], v[244:245], v[44:45] neg_lo:[0,0,1] neg_hi:[0,0,1]
	v_pk_fma_f32 v[46:47], v[28:29], v[242:243], v[46:47] neg_lo:[0,0,1] neg_hi:[0,0,1]
	v_pk_fma_f32 v[48:49], v[26:27], v[244:245], v[48:49]
	v_pk_fma_f32 v[50:51], v[24:25], v[242:243], v[50:51]
	v_pk_fma_f32 v[52:53], v[22:23], v[244:245], v[52:53] neg_lo:[0,0,1] neg_hi:[0,0,1]
	v_pk_fma_f32 v[54:55], v[20:21], v[242:243], v[54:55] neg_lo:[0,0,1] neg_hi:[0,0,1]
	v_pk_fma_f32 v[34:35], v[18:19], v[244:245], v[34:35]
	v_pk_fma_f32 v[32:33], v[16:17], v[242:243], v[32:33]
	v_cndmask_b32_e64 v31, v31, v45, s[0:1]
	v_cndmask_b32_e64 v30, v30, v44, s[0:1]
	v_cndmask_b32_e64 v29, v29, v47, s[0:1]
	v_cndmask_b32_e64 v28, v28, v46, s[0:1]
	v_cndmask_b32_e64 v27, v27, v49, s[0:1]
	v_cndmask_b32_e64 v26, v26, v48, s[0:1]
	v_cndmask_b32_e64 v25, v25, v51, s[0:1]
	v_cndmask_b32_e64 v24, v24, v50, s[0:1]
	v_cndmask_b32_e32 v23, v23, v53, vcc
	v_cndmask_b32_e32 v22, v22, v52, vcc
	v_cndmask_b32_e32 v21, v21, v55, vcc
	v_cndmask_b32_e32 v20, v20, v54, vcc
	v_cndmask_b32_e32 v19, v19, v35, vcc
	v_cndmask_b32_e32 v18, v18, v34, vcc
	v_cndmask_b32_e32 v17, v17, v33, vcc
	v_cndmask_b32_e32 v16, v16, v32, vcc
	v_pk_mul_f32 v[32:33], v[28:29], s[50:51] op_sel_hi:[1,0]
	v_pk_mul_f32 v[34:35], v[30:31], s[50:51] op_sel_hi:[1,0]
	v_pk_mul_f32 v[36:37], v[24:25], s[50:51] op_sel_hi:[1,0]
	v_pk_mul_f32 v[38:39], v[26:27], s[50:51] op_sel_hi:[1,0]
	v_pk_mul_f32 v[44:45], v[20:21], s[50:51] op_sel_hi:[1,0]
	v_pk_mul_f32 v[46:47], v[22:23], s[50:51] op_sel_hi:[1,0]
	v_pk_mul_f32 v[48:49], v[16:17], s[50:51] op_sel_hi:[1,0]
	v_pk_mul_f32 v[50:51], v[18:19], s[50:51] op_sel_hi:[1,0]
	v_cndmask_b32_e64 v31, v31, v35, s[6:7]
	v_cndmask_b32_e64 v30, v30, v34, s[6:7]
	v_cndmask_b32_e64 v29, v29, v33, s[6:7]
	v_cndmask_b32_e64 v28, v28, v32, s[6:7]
	v_cndmask_b32_e64 v27, v27, v39, s[6:7]
	v_cndmask_b32_e64 v26, v26, v38, s[6:7]
	v_cndmask_b32_e64 v25, v25, v37, s[6:7]
	v_cndmask_b32_e64 v24, v24, v36, s[6:7]
	v_cndmask_b32_e64 v23, v23, v47, s[8:9]
	v_cndmask_b32_e64 v22, v22, v46, s[8:9]
	v_cndmask_b32_e64 v21, v21, v45, s[8:9]
	v_cndmask_b32_e64 v20, v20, v44, s[8:9]
	v_cndmask_b32_e64 v32, v19, v51, s[8:9]
	v_cndmask_b32_e64 v33, v18, v50, s[8:9]
	v_cndmask_b32_e64 v34, v17, v49, s[8:9]
	v_cndmask_b32_e64 v35, v16, v48, s[8:9]
	v_cvt_pk_bf16_f32 v16, v28, v29
	v_cvt_pk_bf16_f32 v17, v30, v31
	v_cvt_pk_bf16_f32 v18, v24, v25
	v_cvt_pk_bf16_f32 v19, v26, v27
	v_cvt_pk_bf16_f32 v20, v20, v21
	v_cvt_pk_bf16_f32 v21, v22, v23
	v_cvt_pk_bf16_f32 v22, v35, v34
	v_cvt_pk_bf16_f32 v23, v33, v32
	global_store_dwordx4 v[40:41], v[16:19], off
	global_store_dwordx4 v[40:41], v[20:23], off offset:256
	v_or_b32_e32 v24, s55, v154
	s_andn2_b64 vcc, exec, s[4:5]
	v_cmp_gt_i32_e64 s[0:1], s81, v24
	v_mad_i64_i32 v[24:25], s[4:5], v24, s90, v[138:139]
	s_and_b64 s[4:5], s[64:65], s[0:1]
	s_and_b64 s[0:1], s[66:67], s[0:1]
	v_lshl_add_u64 v[24:25], v[24:25], 0, s[70:71]
	s_waitcnt vmcnt(15)
	v_pk_mul_f32 v[26:27], v[10:11], v[248:249]
	v_pk_mul_f32 v[28:29], v[8:9], v[246:247]
	v_pk_mul_f32 v[30:31], v[14:15], v[248:249]
	v_pk_mul_f32 v[32:33], v[12:13], v[246:247]
	v_pk_mul_f32 v[34:35], v[2:3], v[248:249]
	v_pk_mul_f32 v[36:37], v[0:1], v[246:247]
	v_pk_mul_f32 v[18:19], v[6:7], v[248:249]
	v_pk_mul_f32 v[16:17], v[4:5], v[246:247]
	s_waitcnt vmcnt(14)
	v_pk_fma_f32 v[26:27], v[14:15], v[252:253], v[26:27] neg_lo:[0,0,1] neg_hi:[0,0,1]
	v_pk_fma_f32 v[28:29], v[12:13], v[250:251], v[28:29] neg_lo:[0,0,1] neg_hi:[0,0,1]
	v_pk_fma_f32 v[30:31], v[10:11], v[252:253], v[30:31]
	v_pk_fma_f32 v[32:33], v[8:9], v[250:251], v[32:33]
	v_pk_fma_f32 v[34:35], v[6:7], v[252:253], v[34:35] neg_lo:[0,0,1] neg_hi:[0,0,1]
	v_pk_fma_f32 v[36:37], v[4:5], v[250:251], v[36:37] neg_lo:[0,0,1] neg_hi:[0,0,1]
	v_pk_fma_f32 v[18:19], v[2:3], v[252:253], v[18:19]
	v_pk_fma_f32 v[16:17], v[0:1], v[250:251], v[16:17]
	v_cndmask_b32_e64 v15, v15, v27, s[4:5]
	v_cndmask_b32_e64 v14, v14, v26, s[4:5]
	v_cndmask_b32_e64 v13, v13, v29, s[4:5]
	v_cndmask_b32_e64 v12, v12, v28, s[4:5]
	v_cndmask_b32_e64 v11, v11, v31, s[4:5]
	v_cndmask_b32_e64 v10, v10, v30, s[4:5]
	v_cndmask_b32_e64 v9, v9, v33, s[4:5]
	v_cndmask_b32_e64 v8, v8, v32, s[4:5]
	v_cndmask_b32_e64 v7, v7, v35, s[0:1]
	v_cndmask_b32_e64 v6, v6, v34, s[0:1]
	v_cndmask_b32_e64 v5, v5, v37, s[0:1]
	v_cndmask_b32_e64 v4, v4, v36, s[0:1]
	v_cndmask_b32_e64 v3, v3, v19, s[0:1]
	v_cndmask_b32_e64 v2, v2, v18, s[0:1]
	v_cndmask_b32_e64 v1, v1, v17, s[0:1]
	v_cndmask_b32_e64 v0, v0, v16, s[0:1]
	v_pk_mul_f32 v[16:17], v[12:13], s[50:51] op_sel_hi:[1,0]
	v_pk_mul_f32 v[18:19], v[14:15], s[50:51] op_sel_hi:[1,0]
	v_pk_mul_f32 v[20:21], v[8:9], s[50:51] op_sel_hi:[1,0]
	v_pk_mul_f32 v[22:23], v[10:11], s[50:51] op_sel_hi:[1,0]
	v_pk_mul_f32 v[26:27], v[4:5], s[50:51] op_sel_hi:[1,0]
	v_pk_mul_f32 v[28:29], v[6:7], s[50:51] op_sel_hi:[1,0]
	v_pk_mul_f32 v[30:31], v[0:1], s[50:51] op_sel_hi:[1,0]
	v_pk_mul_f32 v[32:33], v[2:3], s[50:51] op_sel_hi:[1,0]
	v_cndmask_b32_e64 v15, v15, v19, s[6:7]
	v_cndmask_b32_e64 v14, v14, v18, s[6:7]
	v_cndmask_b32_e64 v13, v13, v17, s[6:7]
	v_cndmask_b32_e64 v12, v12, v16, s[6:7]
	v_cndmask_b32_e64 v11, v11, v23, s[6:7]
	v_cndmask_b32_e64 v10, v10, v22, s[6:7]
	v_cndmask_b32_e64 v9, v9, v21, s[6:7]
	v_cndmask_b32_e64 v8, v8, v20, s[6:7]
	v_cndmask_b32_e64 v7, v7, v29, s[8:9]
	v_cndmask_b32_e64 v6, v6, v28, s[8:9]
	v_cndmask_b32_e64 v5, v5, v27, s[8:9]
	v_cndmask_b32_e64 v4, v4, v26, s[8:9]
	v_cndmask_b32_e64 v16, v3, v33, s[8:9]
	v_cndmask_b32_e64 v17, v2, v32, s[8:9]
	v_cndmask_b32_e64 v18, v1, v31, s[8:9]
	v_cndmask_b32_e64 v19, v0, v30, s[8:9]
	v_cvt_pk_bf16_f32 v0, v12, v13
	v_cvt_pk_bf16_f32 v1, v14, v15
	v_cvt_pk_bf16_f32 v2, v8, v9
	v_cvt_pk_bf16_f32 v3, v10, v11
	s_mov_b64 s[0:1], -1
	v_cvt_pk_bf16_f32 v4, v4, v5
	v_cvt_pk_bf16_f32 v5, v6, v7
	v_cvt_pk_bf16_f32 v6, v19, v18
	v_cvt_pk_bf16_f32 v7, v17, v16
	global_store_dwordx4 v[24:25], v[0:3], off
	global_store_dwordx4 v[24:25], v[4:7], off offset:256
	s_cbranch_vccnz .LBB0_181
	s_andn2_b64 vcc, exec, s[42:43]
	s_cbranch_vccnz .LBB0_180
	s_barrier
	s_branch .LBB0_180
